# diff-attn: second-half exp/cvt (P for the s2=1 MFMAs) issued inside the s2=0 MFMA run
# baseline (speedup 1.0000x reference)
; template <int NMAP, int VD, bool SWA> ...
;     ...
;         for (int mp = 0; mp < NMAP; ++mp) {
;             if (i == 0 || __builtin_amdgcn_ballot_w64(mx[mp] > 8.0f) != 0ull) {
;                 const float delta = (i == 0) ? mx[mp] : fmaxf(mx[mp], 0.f), alpha = (i == 0) ? 0.f : __builtin_amdgcn_exp2f(-delta);
;                 mrun[mp] += delta; negm[mp] = (f32x4){-mrun[mp], -mrun[mp], -mrun[mp], -mrun[mp]}; lsum[mp] *= alpha;
; #pragma unroll
;                 for (int kt = 0; kt < 4; ++kt) sacc[mp][kt] = sacc[mp][kt] - delta;
; #pragma unroll
;                 for (int et = 0; et < NET; ++et) oacc[mp][et] = oacc[mp][et] * alpha;
;             }
.LBB0_123:
	ds_bpermute_b32 v58, v179, v225
	s_waitcnt lgkmcnt(0)
	v_max_f32_e32 v225, v225, v58
	ds_bpermute_b32 v58, v180, v225
	s_waitcnt lgkmcnt(0)
	v_max_f32_e32 v225, v225, v58
	v_max_f32_e32 v58, v225, v225
	v_max_f32_e32 v61, 0, v58
	v_exp_f32_e64 v60, -v61
	v_sub_f32_e32 v142, v142, v61
	v_sub_f32_e32 v143, v143, v61
	v_sub_f32_e32 v144, v144, v61
	v_pk_add_f32 v[58:59], v[164:165], v[60:61]
	v_pk_mul_f32 v[164:165], v[164:165], v[60:61]
	v_xor_b32_e32 v58, 0x80000000, v59
	v_mov_b32_e32 v165, v59
	v_sub_f32_e32 v145, v145, v61
	v_sub_f32_e32 v138, v138, v61
	v_sub_f32_e32 v139, v139, v61
	v_sub_f32_e32 v140, v140, v61
	v_sub_f32_e32 v141, v141, v61
	v_sub_f32_e32 v118, v118, v61
	v_sub_f32_e32 v119, v119, v61
	v_sub_f32_e32 v120, v120, v61
	v_sub_f32_e32 v121, v121, v61
	v_sub_f32_e32 v114, v114, v61
	v_sub_f32_e32 v115, v115, v61
	v_sub_f32_e32 v116, v116, v61
	v_sub_f32_e32 v117, v117, v61
	v_pk_mul_f32 v[84:85], v[84:85], v[60:61] op_sel_hi:[1,0]
	v_pk_mul_f32 v[82:83], v[82:83], v[60:61] op_sel_hi:[1,0]
	v_pk_mul_f32 v[72:73], v[72:73], v[60:61] op_sel_hi:[1,0]
	v_pk_mul_f32 v[70:71], v[70:71], v[60:61] op_sel_hi:[1,0]
	v_pk_mul_f32 v[64:65], v[64:65], v[60:61] op_sel_hi:[1,0]
	v_pk_mul_f32 v[62:63], v[62:63], v[60:61] op_sel_hi:[1,0]
	v_pk_mul_f32 v[52:53], v[52:53], v[60:61] op_sel_hi:[1,0]
	v_pk_mul_f32 v[50:51], v[50:51], v[60:61] op_sel_hi:[1,0]
	v_pk_mul_f32 v[44:45], v[44:45], v[60:61] op_sel_hi:[1,0]
	v_pk_mul_f32 v[42:43], v[42:43], v[60:61] op_sel_hi:[1,0]
	v_pk_mul_f32 v[36:37], v[36:37], v[60:61] op_sel_hi:[1,0]
	v_pk_mul_f32 v[34:35], v[34:35], v[60:61] op_sel_hi:[1,0]
	v_pk_mul_f32 v[28:29], v[28:29], v[60:61] op_sel_hi:[1,0]
	v_pk_mul_f32 v[26:27], v[26:27], v[60:61] op_sel_hi:[1,0]
	v_pk_mul_f32 v[20:21], v[20:21], v[60:61] op_sel_hi:[1,0]
	v_pk_mul_f32 v[18:19], v[18:19], v[60:61] op_sel_hi:[1,0]
	v_pk_mul_f32 v[248:249], v[248:249], v[60:61] op_sel_hi:[1,0]
	v_pk_mul_f32 v[250:251], v[250:251], v[60:61] op_sel_hi:[1,0]
	v_mov_b32_e32 v59, v58
	v_mov_b32_e32 v60, v58
	v_mov_b32_e32 v61, v58
	v_mov_b32_e32 v110, v58
	v_mov_b32_e32 v111, v58
	v_mov_b32_e32 v112, v58
	v_mov_b32_e32 v113, v58
; __device__ __forceinline__ unsigned cvt_pk_bf16(float lo, float hi) { unsigned r; asm volatile("v_cvt_pk_bf16_f32 %0, %1, %2" : "=v"(r) : "v"(lo), "v"(hi)); return r; }
; template <int NMAP, int VD, bool SWA> ...
;     ...
;             float ps = 0.f;
; #pragma unroll
;             for (int kt = 0; kt < 4; ++kt)
; #pragma unroll
;                 for (int r = 0; r < 4; ++r) { const float p = __builtin_amdgcn_exp2f(sacc[mp][kt][r]); sacc[mp][kt][r] = p; ps += p; }
;             lsum[mp] += ps;
; #pragma unroll
;             for (int s2 = 0; s2 < 2; ++s2) {
;                 u32x4 pk; pk.x = cvt_pk_bf16(sacc[mp][2 * s2][0], sacc[mp][2 * s2][1]); pk.y = cvt_pk_bf16(sacc[mp][2 * s2][2], sacc[mp][2 * s2][3]);
;                 pk.z = cvt_pk_bf16(sacc[mp][2 * s2 + 1][0], sacc[mp][2 * s2 + 1][1]); pk.w = cvt_pk_bf16(sacc[mp][2 * s2 + 1][2], sacc[mp][2 * s2 + 1][3]);
;                 pf[mp][s2] = __builtin_bit_cast(bf16x8, pk);
;             }
;         }
; #pragma unroll
;         for (int idx = 0; idx < 2 * NET; ++idx) {
;             const int et = idx % NET, s2 = idx / NET;
;             const bf16x8 cur = va[idx & 3];
;             if (idx + 4 < 2 * NET) ATT_LDV(va[idx & 3], idx + 4);
; #pragma unroll
;             for (int mp = 0; mp < NMAP; ++mp) oacc[mp][et] = __builtin_amdgcn_mfma_f32_16x16x32_bf16(cur, pf[mp][s2], oacc[mp][et], 0, 0, 0);
;         }
.LBB0_124:
	v_exp_f32_e32 v142, v142
	v_exp_f32_e32 v143, v143
	v_exp_f32_e32 v144, v144
	v_exp_f32_e32 v145, v145
	v_exp_f32_e32 v202, v138
	v_exp_f32_e32 v203, v139
	v_exp_f32_e32 v225, v140
	v_exp_f32_e32 v226, v141
	v_cvt_pk_bf16_f32 v138, v142, v143
	v_cvt_pk_bf16_f32 v139, v144, v145
	v_cvt_pk_bf16_f32 v140, v202, v203
	v_cvt_pk_bf16_f32 v141, v225, v226
	v_exp_f32_e32 v227, v118
	v_exp_f32_e32 v228, v119
	v_exp_f32_e32 v229, v120
	v_exp_f32_e32 v230, v121
	v_mfma_f32_16x16x32_bf16 v[244:247], v[240:243], v[150:153], v[244:247]
	v_mfma_f32_16x16x32_bf16 v[248:251], v[240:243], v[138:141], v[248:251]
	ds_read_b64_tr_b16 v[120:121], v212 offset:23168
	ds_read_b64_tr_b16 v[118:119], v212 offset:18560
	v_mfma_f32_16x16x32_bf16 v[54:57], v[122:125], v[150:153], v[54:57]
	v_exp_f32_e32 v214, v146
	v_exp_f32_e32 v215, v147
	s_add_u32 s8, s8, 0x4000
	s_cmp_lg_u32 s11, s8
	v_mfma_f32_16x16x32_bf16 v[50:53], v[122:125], v[138:141], v[50:53]
	v_exp_f32_e32 v216, v148
	v_exp_f32_e32 v156, v149
	ds_read_b64_tr_b16 v[122:123], v212 offset:18592
	ds_read_b64_tr_b16 v[124:125], v212 offset:23200
	s_waitcnt lgkmcnt(2)
	v_mfma_f32_16x16x32_bf16 v[46:49], v[118:121], v[150:153], v[46:49]
	v_exp_f32_e32 v157, v94
	v_mfma_f32_16x16x32_bf16 v[42:45], v[118:121], v[138:141], v[42:45]
	v_exp_f32_e32 v213, v95
	ds_read_b64_tr_b16 v[118:119], v212 offset:18624
	s_waitcnt lgkmcnt(1)
	v_mfma_f32_16x16x32_bf16 v[38:41], v[122:125], v[150:153], v[38:41]
	v_exp_f32_e32 v154, v96
	v_mfma_f32_16x16x32_bf16 v[34:37], v[122:125], v[138:141], v[34:37]
	v_exp_f32_e32 v155, v97
	ds_read_b64_tr_b16 v[120:121], v212 offset:23232
	ds_read_b64_tr_b16 v[122:123], v212 offset:18656
	ds_read_b64_tr_b16 v[124:125], v212 offset:23264
	v_mfma_f32_16x16x32_bf16 v[66:69], v[126:129], v[150:153], v[66:69]
	v_cvt_pk_bf16_f32 v146, v214, v215
	v_mfma_f32_16x16x32_bf16 v[62:65], v[126:129], v[138:141], v[62:65]
	v_cvt_pk_bf16_f32 v147, v216, v156
	v_cvt_pk_bf16_f32 v148, v157, v213
	s_waitcnt lgkmcnt(2)
	v_mfma_f32_16x16x32_bf16 v[30:33], v[118:121], v[150:153], v[30:33]
	v_cvt_pk_bf16_f32 v149, v154, v155
	v_mfma_f32_16x16x32_bf16 v[26:29], v[118:121], v[138:141], v[26:29]
	v_exp_f32_e32 v231, v114
	v_exp_f32_e32 v232, v115
	ds_read_b64_tr_b16 v[118:119], v212 offset:27648
	ds_read_b64_tr_b16 v[120:121], v212 offset:32256
	v_mfma_f32_16x16x32_bf16 v[78:81], v[134:137], v[150:153], v[78:81]
	v_exp_f32_e32 v233, v116
	v_exp_f32_e32 v234, v117
	v_mfma_f32_16x16x32_bf16 v[82:85], v[134:137], v[138:141], v[82:85]
	v_cvt_pk_bf16_f32 v114, v227, v228
	s_waitcnt lgkmcnt(2)
	v_mfma_f32_16x16x32_bf16 v[22:25], v[122:125], v[150:153], v[22:25]
	v_cvt_pk_bf16_f32 v115, v229, v230
	v_cvt_pk_bf16_f32 v116, v231, v232
	v_mfma_f32_16x16x32_bf16 v[18:21], v[122:125], v[138:141], v[18:21]
	v_cvt_pk_bf16_f32 v117, v233, v234
	s_waitcnt lgkmcnt(0)
	v_mfma_f32_16x16x32_bf16 v[78:81], v[118:121], v[146:149], v[78:81]
	v_mfma_f32_16x16x32_bf16 v[82:85], v[118:121], v[114:117], v[82:85]
	v_mfma_f32_16x16x32_bf16 v[244:247], v[240:243], v[146:149], v[244:247]
	v_mfma_f32_16x16x32_bf16 v[248:251], v[240:243], v[114:117], v[248:251]
	v_mfma_f32_16x16x32_bf16 v[74:77], v[130:133], v[150:153], v[74:77]
	v_mfma_f32_16x16x32_bf16 v[70:73], v[130:133], v[138:141], v[70:73]
	ds_read_b64_tr_b16 v[126:127], v212 offset:27680
	ds_read_b64_tr_b16 v[130:131], v212 offset:27712
	ds_read_b64_tr_b16 v[134:135], v212 offset:27744
	ds_read_b64_tr_b16 v[128:129], v212 offset:32288
	ds_read_b64_tr_b16 v[132:133], v212 offset:32320
	ds_read_b64_tr_b16 v[136:137], v212 offset:32352
	ds_read_b64_tr_b16 v[118:119], v212 offset:27776
	ds_read_b64_tr_b16 v[120:121], v212 offset:32384
	s_waitcnt lgkmcnt(2)
	v_mfma_f32_16x16x32_bf16 v[54:57], v[134:137], v[146:149], v[54:57]
	v_mfma_f32_16x16x32_bf16 v[50:53], v[134:137], v[114:117], v[50:53]
	s_waitcnt lgkmcnt(0)
	v_mfma_f32_16x16x32_bf16 v[46:49], v[118:121], v[146:149], v[46:49]
	v_mfma_f32_16x16x32_bf16 v[42:45], v[118:121], v[114:117], v[42:45]
	v_mfma_f32_16x16x32_bf16 v[74:77], v[126:129], v[146:149], v[74:77]
	v_mfma_f32_16x16x32_bf16 v[70:73], v[126:129], v[114:117], v[70:73]
	v_mfma_f32_16x16x32_bf16 v[66:69], v[130:133], v[146:149], v[66:69]
	v_mfma_f32_16x16x32_bf16 v[62:65], v[130:133], v[114:117], v[62:65]
	ds_read_b64_tr_b16 v[122:123], v212 offset:27808
	ds_read_b64_tr_b16 v[126:127], v212 offset:27840
	ds_read_b64_tr_b16 v[130:131], v212 offset:27872
	ds_read_b64_tr_b16 v[124:125], v212 offset:32416
	ds_read_b64_tr_b16 v[128:129], v212 offset:32448
	ds_read_b64_tr_b16 v[132:133], v212 offset:32480
	s_waitcnt lgkmcnt(0)
	v_mfma_f32_16x16x32_bf16 v[38:41], v[122:125], v[146:149], v[38:41]
	s_barrier
	v_mfma_f32_16x16x32_bf16 v[34:37], v[122:125], v[114:117], v[34:37]
	v_mfma_f32_16x16x32_bf16 v[30:33], v[126:129], v[146:149], v[30:33]
	v_mfma_f32_16x16x32_bf16 v[26:29], v[126:129], v[114:117], v[26:29]
	v_mfma_f32_16x16x32_bf16 v[22:25], v[130:133], v[146:149], v[22:25]
	v_mfma_f32_16x16x32_bf16 v[18:21], v[130:133], v[114:117], v[18:21]
	s_cbranch_scc0 .LBB0_130

; __device__ __forceinline__ unsigned cvt_pk_bf16(float lo, float hi) { unsigned r; asm volatile("v_cvt_pk_bf16_f32 %0, %1, %2" : "=v"(r) : "v"(lo), "v"(hi)); return r; }
; template <int NMAP, int VD, bool SWA> ...
;     ...
;             float ps = 0.f;
; #pragma unroll
;             for (int kt = 0; kt < 4; ++kt)
; #pragma unroll
;                 for (int r = 0; r < 4; ++r) { const float p = __builtin_amdgcn_exp2f(sacc[mp][kt][r]); sacc[mp][kt][r] = p; ps += p; }
;             lsum[mp] += ps;
; #pragma unroll
;             for (int s2 = 0; s2 < 2; ++s2) {
;                 u32x4 pk; pk.x = cvt_pk_bf16(sacc[mp][2 * s2][0], sacc[mp][2 * s2][1]); pk.y = cvt_pk_bf16(sacc[mp][2 * s2][2], sacc[mp][2 * s2][3]);
;                 pk.z = cvt_pk_bf16(sacc[mp][2 * s2 + 1][0], sacc[mp][2 * s2 + 1][1]); pk.w = cvt_pk_bf16(sacc[mp][2 * s2 + 1][2], sacc[mp][2 * s2 + 1][3]);
;                 pf[mp][s2] = __builtin_bit_cast(bf16x8, pk);
;             }
.LBB0_127:
.LBB0_128:
	s_waitcnt lgkmcnt(0)
	v_exp_f32_e32 v224, v154
	v_exp_f32_e32 v223, v155
	v_exp_f32_e32 v220, v156
	v_exp_f32_e32 v221, v157
	v_exp_f32_e32 v222, v150
	v_exp_f32_e32 v217, v151
	v_exp_f32_e32 v218, v152
	v_exp_f32_e32 v219, v153
	v_cmp_lt_f32_e32 vcc, s72, v225
	v_cvt_pk_bf16_f32 v150, v224, v223
	v_cvt_pk_bf16_f32 v151, v220, v221
	v_cvt_pk_bf16_f32 v152, v222, v217
	v_cvt_pk_bf16_f32 v153, v218, v219
	s_cbranch_vccnz .LBB0_123
	s_branch .LBB0_124
